# v69: v61 + P0 LayerNorm rows: the per-layer-embedding row load is issued with the x row loads (one HBM round trip per row instead of two)
# baseline (speedup 1.0000x reference)
; DI unsigned pack2(float lo, float hi) { f32x2_t v = {lo, hi}; bf16x2_t b = __builtin_convertvector(v, bf16x2_t); return __builtin_bit_cast(unsigned, b); }
; DI float wave_sum(float v, int lane) { for (int o = 32; o > 0; o >>= 1) v += shx(v, o, lane); return v; }
; DI void ln_row(const float* src, const float* __restrict__ g, const float* __restrict__ b, float* dstf, bf16_t* dstb, float* stats, int lane) {
;     f32x4 v[4];
; #pragma unroll
;     for (int i = 0; i < 4; ++i) v[i] = *(const f32x4*)(src + i * 256 + lane * 4);
;     float s = 0.f;
; #pragma unroll
;     for (int i = 0; i < 4; ++i) s += (v[i][0] + v[i][1]) + (v[i][2] + v[i][3]);
;     s = wave_sum(s, lane);
;     const float mu = s * (1.f / 1024.f);
;     float q = 0.f;
; #pragma unroll
;     for (int i = 0; i < 4; ++i) { f32x4 d = v[i] - mu; q += (d[0] * d[0] + d[1] * d[1]) + (d[2] * d[2] + d[3] * d[3]); }
;     q = wave_sum(q, lane);
;     const float rstd = rsqrtf(q * (1.f / 1024.f) + 1e-5f);
; __global__ void __launch_bounds__(512, 2) fwd_mega(Params P) {
;     ...
;             const int row = (it - 1984) * 4 + tw;
;             ln_row(P.in[0] + (size_t)row * DM, P.in[2], P.in[3], nullptr, (bf16_t*)(ws + OFF_HB) + (size_t)row * DM, (float*)(ws + OFF_STATS) + row * 2, lane);
;             { const f32x4 pv = *(const f32x4*)(P.in[1] + (size_t)row * 256 + lane * 4); u32x2 w; w.x = pack2(pv[0], pv[1]); w.y = pack2(pv[2], pv[3]);
.LBB0_24:
	v_cmp_lt_u32_e32 vcc, s20, v3
	s_and_saveexec_b64 s[10:11], vcc
	s_xor_b64 s[10:11], exec, s[10:11]
	s_cbranch_execz .LBB0_28
	v_lshl_or_b32 v0, v3, 2, v2
	v_add_u32_e32 v16, 0xffffe100, v0
	v_readlane_b32 s60, v255, 1
	v_lshlrev_b64 v[0:1], 12, v[16:17]
	v_readlane_b32 s61, v255, 2
	v_lshlrev_b32_e32 v52, 4, v21
	v_mov_b32_e32 v53, v17
	v_lshl_add_u64 v[0:1], s[60:61], 0, v[0:1]
	v_lshl_add_u64 v[0:1], v[0:1], 0, v[52:53]
	global_load_dwordx4 v[12:15], v[0:1], off
	global_load_dwordx4 v[8:11], v[0:1], off offset:1024
	global_load_dwordx4 v[4:7], v[0:1], off offset:2048
	s_nop 0
	global_load_dwordx4 v[0:3], v[0:1], off offset:3072
	v_readlane_b32 s62, v255, 3
	v_readlane_b32 s63, v255, 4
	v_lshlrev_b64 v[76:77], 10, v[16:17]
	v_lshlrev_b32_e32 v78, 4, v21
	v_mov_b32_e32 v79, v17
	v_lshl_add_u64 v[76:77], s[62:63], 0, v[76:77]
	v_lshl_add_u64 v[76:77], v[76:77], 0, v[78:79]
	global_load_dwordx4 v[76:79], v[76:77], off
	v_lshlrev_b32_e32 v22, 2, v21
	v_xor_b32_e32 v67, 0x80, v22
	v_xor_b32_e32 v70, 64, v22
	v_xor_b32_e32 v71, 32, v22
	v_xor_b32_e32 v72, 16, v22
	v_xor_b32_e32 v73, 8, v22
	v_readlane_b32 s66, v255, 7
	v_readlane_b32 s67, v255, 8
	v_readlane_b32 s64, v255, 5
	v_readlane_b32 s65, v255, 6
	v_xor_b32_e32 v74, 4, v22
	v_readlane_b32 s62, v255, 3
	v_readlane_b32 s63, v255, 4
	v_readlane_b32 s68, v255, 9
	v_readlane_b32 s69, v255, 10
	v_readlane_b32 s70, v255, 11
	v_readlane_b32 s71, v255, 12
	v_readlane_b32 s72, v255, 13
	v_readlane_b32 s73, v255, 14
	v_readlane_b32 s74, v255, 15
	v_readlane_b32 s75, v255, 16
	s_waitcnt vmcnt(4)
	v_mov_b32_e32 v24, v13
	v_mov_b32_e32 v25, v14
	v_mov_b32_e32 v26, v12
	v_mov_b32_e32 v27, v15
	s_waitcnt vmcnt(3)
	v_mov_b32_e32 v28, v9
	v_mov_b32_e32 v29, v10
	v_mov_b32_e32 v30, v8
	v_mov_b32_e32 v31, v11
	v_pk_add_f32 v[24:25], v[24:25], v[26:27]
	v_pk_add_f32 v[26:27], v[28:29], v[30:31]
	v_add_f32_e32 v23, v24, v25
	v_pk_add_f32 v[24:25], v[26:27], v[26:27] op_sel:[0,1] op_sel_hi:[1,0]
	s_waitcnt vmcnt(2)
	v_add_f32_e32 v32, v4, v5
	v_add_f32_e32 v34, v6, v7
	s_waitcnt vmcnt(1)
	v_mov_b32_e32 v37, v0
	v_mov_b32_e32 v33, v2
	v_mov_b32_e32 v35, v3
	v_add_f32_e32 v36, 0, v23
	v_mov_b32_e32 v25, v1
	v_pk_add_f32 v[28:29], v[32:33], v[34:35]
	v_pk_add_f32 v[24:25], v[36:37], v[24:25]
	s_nop 0
	v_pk_add_f32 v[24:25], v[24:25], v[28:29]
	s_nop 0
	v_add_f32_e32 v23, v24, v25
	ds_bpermute_b32 v24, v67, v23
	s_waitcnt lgkmcnt(0)
	v_add_f32_e32 v23, v23, v24
	ds_bpermute_b32 v24, v70, v23
	s_waitcnt lgkmcnt(0)
	v_add_f32_e32 v23, v23, v24
	ds_bpermute_b32 v24, v71, v23
	s_waitcnt lgkmcnt(0)
	v_add_f32_e32 v23, v23, v24
	ds_bpermute_b32 v24, v72, v23
	s_waitcnt lgkmcnt(0)
	v_add_f32_e32 v23, v23, v24
	ds_bpermute_b32 v40, v73, v23
	global_load_dwordx4 v[24:27], v52, s[66:67] offset:3072
	global_load_dwordx4 v[28:31], v52, s[64:65] offset:3072
	global_load_dwordx4 v[32:35], v52, s[66:67] offset:2048
	global_load_dwordx4 v[36:39], v52, s[64:65] offset:2048
	s_waitcnt lgkmcnt(0)
	v_add_f32_e32 v23, v23, v40
	global_load_dwordx4 v[40:43], v52, s[66:67] offset:1024
	global_load_dwordx4 v[44:47], v52, s[64:65] offset:1024
	global_load_dwordx4 v[48:51], v52, s[66:67]
	s_nop 0
	global_load_dwordx4 v[52:55], v52, s[64:65]
	ds_bpermute_b32 v56, v74, v23
	s_waitcnt lgkmcnt(0)
	v_add_f32_e32 v23, v23, v56
	v_fmamk_f32 v13, v23, 0xba800000, v13
	v_fmamk_f32 v12, v23, 0xba800000, v12
	v_fmamk_f32 v15, v23, 0xba800000, v15
	v_fmac_f32_e32 v14, 0xba800000, v23
	v_fmamk_f32 v9, v23, 0xba800000, v9
	v_fmamk_f32 v8, v23, 0xba800000, v8
	v_fmamk_f32 v11, v23, 0xba800000, v11
	v_fmac_f32_e32 v10, 0xba800000, v23
	v_fmamk_f32 v57, v23, 0xba800000, v3
	v_fmamk_f32 v56, v23, 0xba800000, v2
	v_pk_mul_f32 v[2:3], v[14:15], v[14:15]
	v_pk_mul_f32 v[58:59], v[12:13], v[12:13]
	v_pk_mul_f32 v[60:61], v[10:11], v[10:11]
	v_pk_mul_f32 v[62:63], v[8:9], v[8:9]
	v_fmamk_f32 v4, v23, 0xba800000, v4
	v_fmac_f32_e32 v6, 0xba800000, v23
	v_pk_mov_b32 v[68:69], v[58:59], v[2:3] op_sel:[1,0]
	v_mov_b32_e32 v59, v3
	v_pk_mov_b32 v[2:3], v[62:63], v[60:61] op_sel:[1,0]
	v_mov_b32_e32 v63, v61
	v_fmamk_f32 v5, v23, 0xba800000, v5
	v_fmamk_f32 v7, v23, 0xba800000, v7
	v_mul_f32_e32 v64, v4, v4
	v_mul_f32_e32 v66, v6, v6
	v_pk_add_f32 v[58:59], v[68:69], v[58:59]
	v_pk_add_f32 v[2:3], v[2:3], v[62:63]
	v_fmamk_f32 v1, v23, 0xba800000, v1
	v_fmac_f32_e32 v0, 0xba800000, v23
	v_pk_fma_f32 v[60:61], v[4:5], v[4:5], v[64:65] op_sel_hi:[1,1,0]
	v_pk_fma_f32 v[64:65], v[6:7], v[6:7], v[66:67] op_sel_hi:[1,1,0]
	v_pk_add_f32 v[58:59], v[58:59], v[58:59] op_sel_hi:[0,1]
	v_pk_add_f32 v[2:3], v[2:3], v[2:3] op_sel_hi:[0,1]
	v_mul_f32_e32 v60, v0, v0
	v_mul_f32_e32 v64, v1, v1
	v_mul_f32_e32 v58, v56, v56
	v_mul_f32_e32 v2, v57, v57
	v_pk_add_f32 v[60:61], v[60:61], v[64:65]
	v_pk_add_f32 v[2:3], v[58:59], v[2:3]
	s_nop 0
	v_pk_add_f32 v[2:3], v[60:61], v[2:3]
	s_nop 0
	v_add_f32_e32 v2, v2, v3
	ds_bpermute_b32 v3, v67, v2
	s_waitcnt lgkmcnt(0)
; DI unsigned pack2(float lo, float hi) { f32x2_t v = {lo, hi}; bf16x2_t b = __builtin_convertvector(v, bf16x2_t); return __builtin_bit_cast(unsigned, b); }
; DI float wave_sum(float v, int lane) { for (int o = 32; o > 0; o >>= 1) v += shx(v, o, lane); return v; }
; DI void ln_row(const float* src, const float* __restrict__ g, const float* __restrict__ b, float* dstf, bf16_t* dstb, float* stats, int lane) {
;     ...
;     q = wave_sum(q, lane);
;     const float rstd = rsqrtf(q * (1.f / 1024.f) + 1e-5f);
;     f32x4 gv[4], bv[4];
; #pragma unroll
;     for (int i = 0; i < 4; ++i) { gv[i] = *(const f32x4*)(g + i * 256 + lane * 4); bv[i] = *(const f32x4*)(b + i * 256 + lane * 4); }
; #pragma unroll
;     for (int i = 0; i < 4; ++i) {
;         const f32x4 gg = gv[i], bb = bv[i];
;         const f32x4 o = (v[i] - mu) * rstd * gg + bb;
;         if (dstf) *(f32x4*)(dstf + i * 256 + lane * 4) = o;
;         if (dstb) { u32x2 w; w.x = pack2(o[0], o[1]); w.y = pack2(o[2], o[3]); *(u32x2*)(dstb + i * 256 + lane * 4) = w; }
;     }
;     if (stats && lane == 0) { stats[0] = mu; stats[1] = rstd; }
; __global__ void __launch_bounds__(512, 2) fwd_mega(Params P) {
;     ...
;             { const f32x4 pv = *(const f32x4*)(P.in[1] + (size_t)row * 256 + lane * 4); u32x2 w; w.x = pack2(pv[0], pv[1]); w.y = pack2(pv[2], pv[3]);
;               *(u32x2*)((bf16_t*)(ws + OFF_PB) + (size_t)row * 256 + lane * 4) = w; }
	v_add_f32_e32 v2, v2, v3
	ds_bpermute_b32 v3, v70, v2
	s_waitcnt lgkmcnt(0)
	v_add_f32_e32 v2, v2, v3
	ds_bpermute_b32 v3, v71, v2
	s_waitcnt lgkmcnt(0)
	v_add_f32_e32 v2, v2, v3
	ds_bpermute_b32 v3, v72, v2
	s_waitcnt lgkmcnt(0)
	v_add_f32_e32 v2, v2, v3
	ds_bpermute_b32 v3, v73, v2
	s_waitcnt lgkmcnt(0)
	v_add_f32_e32 v58, v2, v3
	ds_bpermute_b32 v59, v74, v58
	v_lshlrev_b32_e32 v2, 3, v21
	v_mov_b32_e32 v3, v17
	s_waitcnt lgkmcnt(0)
	v_add_f32_e32 v58, v58, v59
	v_fmamk_f32 v58, v58, 0x3a800000, v18
	v_mul_f32_e32 v59, 0x4b800000, v58
	v_cmp_gt_f32_e32 vcc, s21, v58
	s_nop 1
	v_cndmask_b32_e32 v58, v58, v59, vcc
	v_rsq_f32_e32 v60, v58
	v_lshlrev_b64 v[58:59], 11, v[16:17]
	v_lshl_add_u64 v[58:59], s[0:1], 0, v[58:59]
	v_lshl_add_u64 v[58:59], v[58:59], 0, v[2:3]
	v_mul_f32_e32 v2, 0x45800000, v60
	v_cndmask_b32_e32 v2, v60, v2, vcc
	v_pk_mul_f32 v[12:13], v[12:13], v[2:3] op_sel_hi:[1,0]
	v_pk_mul_f32 v[14:15], v[14:15], v[2:3] op_sel_hi:[1,0]
	v_pk_mul_f32 v[8:9], v[8:9], v[2:3] op_sel_hi:[1,0]
	v_pk_mul_f32 v[10:11], v[10:11], v[2:3] op_sel_hi:[1,0]
	v_pk_mul_f32 v[4:5], v[4:5], v[2:3] op_sel_hi:[1,0]
	v_pk_mul_f32 v[6:7], v[6:7], v[2:3] op_sel_hi:[1,0]
	v_pk_mul_f32 v[0:1], v[0:1], v[2:3] op_sel_hi:[1,0]
	v_pk_mul_f32 v[56:57], v[56:57], v[2:3] op_sel_hi:[1,0]
	s_waitcnt vmcnt(0)
	v_pk_fma_f32 v[14:15], v[54:55], v[14:15], v[50:51]
	v_pk_fma_f32 v[12:13], v[52:53], v[12:13], v[48:49]
	v_pk_fma_f32 v[10:11], v[46:47], v[10:11], v[42:43]
	v_pk_fma_f32 v[8:9], v[44:45], v[8:9], v[40:41]
	v_pk_fma_f32 v[6:7], v[38:39], v[6:7], v[34:35]
	v_pk_fma_f32 v[4:5], v[36:37], v[4:5], v[32:33]
	v_pk_fma_f32 v[26:27], v[30:31], v[56:57], v[26:27]
	v_pk_fma_f32 v[0:1], v[28:29], v[0:1], v[24:25]
	v_cvt_pk_bf16_f32 v12, v12, v13
	v_cvt_pk_bf16_f32 v13, v14, v15
	v_cmp_eq_u32_e32 vcc, 0, v21
	v_cvt_pk_bf16_f32 v8, v8, v9
	v_cvt_pk_bf16_f32 v9, v10, v11
	v_cvt_pk_bf16_f32 v4, v4, v5
	v_cvt_pk_bf16_f32 v5, v6, v7
	v_cvt_pk_bf16_f32 v0, v0, v1
	v_cvt_pk_bf16_f32 v1, v26, v27
	global_store_dwordx2 v[58:59], v[12:13], off
	global_store_dwordx2 v[58:59], v[8:9], off offset:512
	global_store_dwordx2 v[58:59], v[4:5], off offset:1024
	global_store_dwordx2 v[58:59], v[0:1], off offset:1536
	s_and_saveexec_b64 s[12:13], vcc
	s_cbranch_execz .LBB0_27
	v_lshlrev_b32_e32 v4, 1, v16
	v_mov_b32_e32 v5, v17
	v_mul_f32_e32 v0, 0x3a800000, v23
	v_lshl_add_u64 v[4:5], v[4:5], 2, s[2:3]
	v_mov_b32_e32 v1, v2
	global_store_dwordx2 v[4:5], v[0:1], off
.LBB0_27:
	s_or_b64 exec, exec, s[12:13]
	v_readlane_b32 s60, v255, 1
	v_lshlrev_b64 v[0:1], 10, v[16:17]
	v_readlane_b32 s62, v255, 3
	v_readlane_b32 s63, v255, 4
	v_lshlrev_b32_e32 v2, 2, v22
	v_mov_b32_e32 v3, v17
	v_lshl_add_u64 v[0:1], s[62:63], 0, v[0:1]
	v_lshl_add_u64 v[0:1], v[0:1], 0, v[2:3]
	v_lshlrev_b64 v[4:5], 9, v[16:17]
	v_lshlrev_b32_e32 v16, 1, v22
	v_lshl_add_u64 v[4:5], s[4:5], 0, v[4:5]
	v_readlane_b32 s61, v255, 2
	v_readlane_b32 s64, v255, 5
	v_readlane_b32 s65, v255, 6
	v_readlane_b32 s66, v255, 7
	v_readlane_b32 s67, v255, 8
	v_readlane_b32 s68, v255, 9
	v_readlane_b32 s69, v255, 10
	v_readlane_b32 s70, v255, 11
	v_readlane_b32 s71, v255, 12
	v_readlane_b32 s72, v255, 13
	v_readlane_b32 s73, v255, 14
	v_readlane_b32 s74, v255, 15
	v_readlane_b32 s75, v255, 16
	s_waitcnt vmcnt(5)
	v_cvt_pk_bf16_f32 v0, v76, v77
	v_cvt_pk_bf16_f32 v1, v78, v79
	v_lshl_add_u64 v[2:3], v[4:5], 0, v[16:17]
	global_store_dwordx2 v[2:3], v[0:1], off
